# P4 in-proj channel-major tiles: hand-written fused-norm epilogue, per-wave LDS transpose (xor-swizzled) so PT stores are full 128-byte lines (16 dwordx4 instead of 32 dwordx2 per wave)
# speedup vs baseline: 1.0281x; 1.0096x over previous
; DEVI unsigned pk_bf16(float lo, float hi) { unsigned r; asm volatile("v_cvt_pk_bf16_f32 %0, %1, %2" : "=v"(r) : "v"(lo), "v"(hi)); return r; }
; template <class Epi>
; DEVI void gemm_phase(const Params& p, const u16* __restrict__ A, const u16* __restrict__ Bt, const int M, const int N, const int K, const int Msplit, const Epi& epi) {
;     ...
;       for (int ai = 0; ai < 2; ++ai)
; #pragma unroll
;         for (int bj = 0; bj < 2; ++bj) {
;           const int colb = bcol + bj * HALF + wc2 * 32;
;           typename Epi::Pre pre;
;           if constexpr (Epi::NRM || Epi::SQ) epi.preload(pre, brow, colb, wr2, fr2, fq2, nrm, slcur);
; #pragma unroll
;           for (int m = 0; m < 4; ++m) {
;             const int rloc = ai * HALF + wr2 * 64 + m * 16;
;             if constexpr (Epi::SQ) epi(brow + rloc + fr2, colb, fq2, acc[ai][bj][m][0], acc[ai][bj][m][1], sq[ai * 4 + m], slcur, pre);
;             else if constexpr (Epi::TR) { float rv = 1.f; if (nrm) rv = rl[rloc + fr2]; epi(brow + rloc + fr2, colb, fq2, acc[ai][bj][m][0], acc[ai][bj][m][1], rv, nrm, pre); }
;             else { f32x4 rv = {1.f, 1.f, 1.f, 1.f}; if (nrm) rv = *(const f32x4*)(rl + rloc + fq2 * 4); epi(brow + rloc + fq2 * 4, colb, fr2, acc[ai][bj][m][0], acc[ai][bj][m][1], rv, nrm, pre); }
;   DEVI void preload(Pre& q, int brow, int colb, int wr, int fr, int fq, bool nrm, int) const {
;     const int r = brow < TL ? (brow >> 12) : 8;
;     q.s0 = nrm ? sw[r * 2048 + colb + fr] : 0.f; q.s1 = nrm ? sw[r * 2048 + colb + 16 + fr] : 0.f;
;     q.invrev = exp2f(-(float)fr * (13.287712379549449f / 16.f)) * 0.15915494309189535f;
;   }
;   DEVI void operator()(int row0, int colb, int fr, const f32x4& b0, const f32x4& b1, const f32x4& rv, const bool nrm, const Pre& q) const {
;     f32x4 a0, a1;
; #pragma unroll
;     for (int j = 0; j < 4; ++j) { a0[j] = b0[j] * rv[j] + q.s0; a1[j] = b1[j] * rv[j] + q.s1; }
;     if (colb < 1280 || colb >= 1920) {
; #pragma unroll
;       for (int n = 0; n < 2; ++n) {
;         const int pc = colb + n * 16 + fr; const int ptc = pc < 1280 ? pc : pc - 640;
;         const f32x4& a = n ? a1 : a0;
;         uint2 o; o.x = pk_bf16(a[0], a[1]); o.y = pk_bf16(a[2], a[3]);
;         *(uint2*)(pt + (size_t)ptc * T + row0) = o;
;       }
.Lmy_p4_pt:
	v_mbcnt_lo_u32_b32 v208, -1, 0
	v_mbcnt_hi_u32_b32 v208, -1, v208
	s_lshr_b32 s52, s33, 6
	s_lshr_b32 s53, s52, 2
	s_and_b32 s54, s52, 3
	v_and_b32_e32 v209, 15, v208
	v_lshrrev_b32_e32 v210, 4, v208
	s_lshl_b32 s55, s52, 12
	s_add_u32 s55, s55, 0x20000
	s_cmp_eq_u32 s52, 7
	s_cselect_b32 s55, 0xd000, s55
	v_lshrrev_b32_e32 v211, 1, v210
	v_and_b32_e32 v212, 7, v209
	v_xor_b32_e32 v211, v211, v212
	v_and_b32_e32 v212, 1, v210
	v_lshlrev_b32_e32 v212, 3, v212
	v_lshl_add_u32 v212, v209, 7, v212
	v_add_u32_e32 v212, s55, v212
	v_lshl_add_u32 v184, v211, 4, v212
	v_xor_b32_e32 v148, 2, v211
	v_lshl_add_u32 v185, v148, 4, v212
	v_xor_b32_e32 v148, 4, v211
	v_lshl_add_u32 v186, v148, 4, v212
	v_xor_b32_e32 v148, 6, v211
	v_lshl_add_u32 v187, v148, 4, v212
	v_and_b32_e32 v149, 7, v208
	v_lshrrev_b32_e32 v150, 3, v208
	v_xor_b32_e32 v148, v149, v150
	v_lshlrev_b32_e32 v148, 4, v148
	v_lshl_add_u32 v188, v150, 7, v148
	v_add_u32_e32 v188, s55, v188
	s_lshl_b32 s58, s54, 5
	v_add_u32_e32 v148, s58, v150
	v_mul_u32_u24_e32 v148, 0x11000, v148
	s_lshl_b32 s58, s53, 7
	v_lshl_add_u32 v148, v149, 4, v148
	v_add_u32_e32 v189, s58, v148
	v_add_u32_e32 v190, 0x88000, v189
	s_lshl_b32 s58, s54, 7
	v_lshl_add_u32 v191, v209, 2, s58
	s_lshl_b32 s58, s53, 8
	v_lshl_add_u32 v192, v210, 4, s58
	s_lshr_b32 s58, s16, 4
	s_lshl_b32 s58, s58, 11
	s_add_u32 s58, s58, s40
	s_lshl_b32 s58, s58, 2
	s_add_u32 s44, s4, s58
	s_addc_u32 s45, s5, 0
	s_mul_i32 s58, s40, 0x11000
	s_lshl_b32 s59, s36, 1
	s_add_u32 s58, s58, s59
	s_add_u32 s46, s60, s58
	s_addc_u32 s47, s61, 0
	global_load_dword v128, v191, s[44:45]
	global_load_dword v129, v191, s[44:45] offset:64
	global_load_dword v130, v191, s[44:45] offset:512
	global_load_dword v131, v191, s[44:45] offset:576
	ds_read_b128 v[152:155], v192 offset:49152
	ds_read_b128 v[156:159], v192 offset:49216
	ds_read_b128 v[160:163], v192 offset:49280
	ds_read_b128 v[164:167], v192 offset:49344
	ds_read_b128 v[168:171], v192 offset:49664
	ds_read_b128 v[172:175], v192 offset:49728
	ds_read_b128 v[176:179], v192 offset:49792
	ds_read_b128 v[180:183], v192 offset:49856
	s_waitcnt vmcnt(0) lgkmcnt(0)
	v_fma_f32 v120, v120, v152, v128
	v_fma_f32 v121, v121, v153, v128
	v_fma_f32 v122, v122, v154, v128
	v_fma_f32 v123, v123, v155, v128
	v_fma_f32 v112, v112, v156, v128
	v_fma_f32 v113, v113, v157, v128
	v_fma_f32 v114, v114, v158, v128
	v_fma_f32 v115, v115, v159, v128
	v_fma_f32 v104, v104, v160, v128
	v_fma_f32 v105, v105, v161, v128
	v_fma_f32 v106, v106, v162, v128
	v_fma_f32 v107, v107, v163, v128
	v_fma_f32 v96, v96, v164, v128
	v_fma_f32 v97, v97, v165, v128
	v_fma_f32 v98, v98, v166, v128
	v_fma_f32 v99, v99, v167, v128
	v_cvt_pk_bf16_f32 v120, v120, v121
	v_cvt_pk_bf16_f32 v121, v122, v123
	v_cvt_pk_bf16_f32 v112, v112, v113
	v_cvt_pk_bf16_f32 v113, v114, v115
	v_cvt_pk_bf16_f32 v104, v104, v105
	v_cvt_pk_bf16_f32 v105, v106, v107
	v_cvt_pk_bf16_f32 v96, v96, v97
	v_cvt_pk_bf16_f32 v97, v98, v99
	ds_write_b64 v184, v[120:121]
	ds_write_b64 v185, v[112:113]
	ds_write_b64 v186, v[104:105]
	ds_write_b64 v187, v[96:97]
	v_fma_f32 v124, v124, v152, v129
	v_fma_f32 v125, v125, v153, v129
	v_fma_f32 v126, v126, v154, v129
	v_fma_f32 v127, v127, v155, v129
	v_fma_f32 v116, v116, v156, v129
	v_fma_f32 v117, v117, v157, v129
	v_fma_f32 v118, v118, v158, v129
	v_fma_f32 v119, v119, v159, v129
	v_fma_f32 v108, v108, v160, v129
	v_fma_f32 v109, v109, v161, v129
	v_fma_f32 v110, v110, v162, v129
	v_fma_f32 v111, v111, v163, v129
	v_fma_f32 v100, v100, v164, v129
	v_fma_f32 v101, v101, v165, v129
	v_fma_f32 v102, v102, v166, v129
	v_fma_f32 v103, v103, v167, v129
	v_cvt_pk_bf16_f32 v124, v124, v125
	v_cvt_pk_bf16_f32 v125, v126, v127
	v_cvt_pk_bf16_f32 v116, v116, v117
	v_cvt_pk_bf16_f32 v117, v118, v119
	v_cvt_pk_bf16_f32 v108, v108, v109
	v_cvt_pk_bf16_f32 v109, v110, v111
	v_cvt_pk_bf16_f32 v100, v100, v101
	v_cvt_pk_bf16_f32 v101, v102, v103
	s_waitcnt lgkmcnt(0)
	ds_read_b128 v[132:135], v188
	ds_read_b128 v[136:139], v188 offset:1024
	ds_write_b64 v184, v[124:125] offset:2048
	ds_write_b64 v185, v[116:117] offset:2048
	ds_write_b64 v186, v[108:109] offset:2048
	ds_write_b64 v187, v[100:101] offset:2048
	v_fma_f32 v88, v88, v152, v130
	v_fma_f32 v89, v89, v153, v130
	v_fma_f32 v90, v90, v154, v130
	v_fma_f32 v91, v91, v155, v130
	v_fma_f32 v80, v80, v156, v130
	v_fma_f32 v81, v81, v157, v130
	v_fma_f32 v82, v82, v158, v130
	v_fma_f32 v83, v83, v159, v130
	v_fma_f32 v72, v72, v160, v130
	v_fma_f32 v73, v73, v161, v130
	v_fma_f32 v74, v74, v162, v130
	v_fma_f32 v75, v75, v163, v130
	v_fma_f32 v64, v64, v164, v130
	v_fma_f32 v65, v65, v165, v130
	v_fma_f32 v66, v66, v166, v130
	v_fma_f32 v67, v67, v167, v130
	v_cvt_pk_bf16_f32 v88, v88, v89
	v_cvt_pk_bf16_f32 v89, v90, v91
	v_cvt_pk_bf16_f32 v80, v80, v81
	v_cvt_pk_bf16_f32 v81, v82, v83
	v_cvt_pk_bf16_f32 v72, v72, v73
	v_cvt_pk_bf16_f32 v73, v74, v75
	v_cvt_pk_bf16_f32 v64, v64, v65
	v_cvt_pk_bf16_f32 v65, v66, v67
	s_waitcnt lgkmcnt(0)
	global_store_dwordx4 v189, v[132:135], s[46:47]
	global_store_dwordx4 v190, v[136:139], s[46:47]
	ds_read_b128 v[140:143], v188 offset:2048
	ds_read_b128 v[144:147], v188 offset:3072
	ds_write_b64 v184, v[88:89]
	ds_write_b64 v185, v[80:81]
	ds_write_b64 v186, v[72:73]
	ds_write_b64 v187, v[64:65]
	v_fma_f32 v92, v92, v152, v131
	v_fma_f32 v93, v93, v153, v131
	v_fma_f32 v94, v94, v154, v131
	v_fma_f32 v95, v95, v155, v131
	v_fma_f32 v84, v84, v156, v131
	v_fma_f32 v85, v85, v157, v131
	v_fma_f32 v86, v86, v158, v131
	v_fma_f32 v87, v87, v159, v131
	v_fma_f32 v76, v76, v160, v131
	v_fma_f32 v77, v77, v161, v131
	v_fma_f32 v78, v78, v162, v131
	v_fma_f32 v79, v79, v163, v131
	v_fma_f32 v68, v68, v164, v131
	v_fma_f32 v69, v69, v165, v131
	v_fma_f32 v70, v70, v166, v131
	v_fma_f32 v71, v71, v167, v131
	v_cvt_pk_bf16_f32 v92, v92, v93
	v_cvt_pk_bf16_f32 v93, v94, v95
	v_cvt_pk_bf16_f32 v84, v84, v85
	v_cvt_pk_bf16_f32 v85, v86, v87
	v_cvt_pk_bf16_f32 v76, v76, v77
	v_cvt_pk_bf16_f32 v77, v78, v79
	v_cvt_pk_bf16_f32 v68, v68, v69
	v_cvt_pk_bf16_f32 v69, v70, v71
	s_waitcnt lgkmcnt(0)
; DEVI unsigned pk_bf16(float lo, float hi) { unsigned r; asm volatile("v_cvt_pk_bf16_f32 %0, %1, %2" : "=v"(r) : "v"(lo), "v"(hi)); return r; }
;   DEVI void operator()(int row0, int colb, int fr, const f32x4& b0, const f32x4& b1, const f32x4& rv, const bool nrm, const Pre& q) const {
;     f32x4 a0, a1;
; #pragma unroll
;     for (int j = 0; j < 4; ++j) { a0[j] = b0[j] * rv[j] + q.s0; a1[j] = b1[j] * rv[j] + q.s1; }
;     if (colb < 1280 || colb >= 1920) {
; #pragma unroll
;       for (int n = 0; n < 2; ++n) {
;         const int pc = colb + n * 16 + fr; const int ptc = pc < 1280 ? pc : pc - 640;
;         const f32x4& a = n ? a1 : a0;
;         uint2 o; o.x = pk_bf16(a[0], a[1]); o.y = pk_bf16(a[2], a[3]);
;         *(uint2*)(pt + (size_t)ptc * T + row0) = o;
;       }
	s_add_u32 s38, s46, 0x110000
	s_addc_u32 s39, s47, 0
	global_store_dwordx4 v189, v[140:143], s[38:39]
	global_store_dwordx4 v190, v[144:147], s[38:39]
	ds_read_b128 v[132:135], v188
	ds_read_b128 v[136:139], v188 offset:1024
	ds_write_b64 v184, v[92:93] offset:2048
	ds_write_b64 v185, v[84:85] offset:2048
	ds_write_b64 v186, v[76:77] offset:2048
	ds_write_b64 v187, v[68:69] offset:2048
	v_fma_f32 v56, v56, v168, v128
	v_fma_f32 v57, v57, v169, v128
	v_fma_f32 v58, v58, v170, v128
	v_fma_f32 v59, v59, v171, v128
	v_fma_f32 v48, v48, v172, v128
	v_fma_f32 v49, v49, v173, v128
	v_fma_f32 v50, v50, v174, v128
	v_fma_f32 v51, v51, v175, v128
	v_fma_f32 v40, v40, v176, v128
	v_fma_f32 v41, v41, v177, v128
	v_fma_f32 v42, v42, v178, v128
	v_fma_f32 v43, v43, v179, v128
	v_fma_f32 v32, v32, v180, v128
	v_fma_f32 v33, v33, v181, v128
	v_fma_f32 v34, v34, v182, v128
	v_fma_f32 v35, v35, v183, v128
	v_cvt_pk_bf16_f32 v56, v56, v57
	v_cvt_pk_bf16_f32 v57, v58, v59
	v_cvt_pk_bf16_f32 v48, v48, v49
	v_cvt_pk_bf16_f32 v49, v50, v51
	v_cvt_pk_bf16_f32 v40, v40, v41
	v_cvt_pk_bf16_f32 v41, v42, v43
	v_cvt_pk_bf16_f32 v32, v32, v33
	v_cvt_pk_bf16_f32 v33, v34, v35
	s_waitcnt lgkmcnt(0)
	s_add_u32 s38, s46, 0x880000
	s_addc_u32 s39, s47, 0
	global_store_dwordx4 v189, v[132:135], s[38:39]
	global_store_dwordx4 v190, v[136:139], s[38:39]
	ds_read_b128 v[140:143], v188 offset:2048
	ds_read_b128 v[144:147], v188 offset:3072
	ds_write_b64 v184, v[56:57]
	ds_write_b64 v185, v[48:49]
	ds_write_b64 v186, v[40:41]
	ds_write_b64 v187, v[32:33]
	v_fma_f32 v60, v60, v168, v129
	v_fma_f32 v61, v61, v169, v129
	v_fma_f32 v62, v62, v170, v129
	v_fma_f32 v63, v63, v171, v129
	v_fma_f32 v52, v52, v172, v129
	v_fma_f32 v53, v53, v173, v129
	v_fma_f32 v54, v54, v174, v129
	v_fma_f32 v55, v55, v175, v129
	v_fma_f32 v44, v44, v176, v129
	v_fma_f32 v45, v45, v177, v129
	v_fma_f32 v46, v46, v178, v129
	v_fma_f32 v47, v47, v179, v129
	v_fma_f32 v36, v36, v180, v129
	v_fma_f32 v37, v37, v181, v129
	v_fma_f32 v38, v38, v182, v129
	v_fma_f32 v39, v39, v183, v129
	v_cvt_pk_bf16_f32 v60, v60, v61
	v_cvt_pk_bf16_f32 v61, v62, v63
	v_cvt_pk_bf16_f32 v52, v52, v53
	v_cvt_pk_bf16_f32 v53, v54, v55
	v_cvt_pk_bf16_f32 v44, v44, v45
	v_cvt_pk_bf16_f32 v45, v46, v47
	v_cvt_pk_bf16_f32 v36, v36, v37
	v_cvt_pk_bf16_f32 v37, v38, v39
	s_waitcnt lgkmcnt(0)
	s_add_u32 s38, s46, 0x990000
	s_addc_u32 s39, s47, 0
	global_store_dwordx4 v189, v[140:143], s[38:39]
	global_store_dwordx4 v190, v[144:147], s[38:39]
	ds_read_b128 v[132:135], v188
	ds_read_b128 v[136:139], v188 offset:1024
	ds_write_b64 v184, v[60:61] offset:2048
	ds_write_b64 v185, v[52:53] offset:2048
	ds_write_b64 v186, v[44:45] offset:2048
	ds_write_b64 v187, v[36:37] offset:2048
	v_fma_f32 v24, v24, v168, v130
	v_fma_f32 v25, v25, v169, v130
	v_fma_f32 v26, v26, v170, v130
	v_fma_f32 v27, v27, v171, v130
	v_fma_f32 v16, v16, v172, v130
	v_fma_f32 v17, v17, v173, v130
	v_fma_f32 v18, v18, v174, v130
	v_fma_f32 v19, v19, v175, v130
	v_fma_f32 v8, v8, v176, v130
	v_fma_f32 v9, v9, v177, v130
	v_fma_f32 v10, v10, v178, v130
	v_fma_f32 v11, v11, v179, v130
	v_fma_f32 v0, v0, v180, v130
	v_fma_f32 v1, v1, v181, v130
	v_fma_f32 v2, v2, v182, v130
	v_fma_f32 v3, v3, v183, v130
	v_cvt_pk_bf16_f32 v24, v24, v25
	v_cvt_pk_bf16_f32 v25, v26, v27
	v_cvt_pk_bf16_f32 v16, v16, v17
	v_cvt_pk_bf16_f32 v17, v18, v19
	v_cvt_pk_bf16_f32 v8, v8, v9
	v_cvt_pk_bf16_f32 v9, v10, v11
	v_cvt_pk_bf16_f32 v0, v0, v1
	v_cvt_pk_bf16_f32 v1, v2, v3
	s_waitcnt lgkmcnt(0)
	s_add_u32 s38, s46, 0x100
	s_addc_u32 s39, s47, 0
	global_store_dwordx4 v189, v[132:135], s[38:39]
	global_store_dwordx4 v190, v[136:139], s[38:39]
	ds_read_b128 v[140:143], v188 offset:2048
	ds_read_b128 v[144:147], v188 offset:3072
	ds_write_b64 v184, v[24:25]
	ds_write_b64 v185, v[16:17]
	ds_write_b64 v186, v[8:9]
	ds_write_b64 v187, v[0:1]
	v_fma_f32 v28, v28, v168, v131
	v_fma_f32 v29, v29, v169, v131
	v_fma_f32 v30, v30, v170, v131
	v_fma_f32 v31, v31, v171, v131
	v_fma_f32 v20, v20, v172, v131
	v_fma_f32 v21, v21, v173, v131
	v_fma_f32 v22, v22, v174, v131
	v_fma_f32 v23, v23, v175, v131
	v_fma_f32 v12, v12, v176, v131
	v_fma_f32 v13, v13, v177, v131
	v_fma_f32 v14, v14, v178, v131
	v_fma_f32 v15, v15, v179, v131
	v_fma_f32 v4, v4, v180, v131
	v_fma_f32 v5, v5, v181, v131
	v_fma_f32 v6, v6, v182, v131
	v_fma_f32 v7, v7, v183, v131
	v_cvt_pk_bf16_f32 v28, v28, v29
	v_cvt_pk_bf16_f32 v29, v30, v31
	v_cvt_pk_bf16_f32 v20, v20, v21
	v_cvt_pk_bf16_f32 v21, v22, v23
	v_cvt_pk_bf16_f32 v12, v12, v13
	v_cvt_pk_bf16_f32 v13, v14, v15
	v_cvt_pk_bf16_f32 v4, v4, v5
	v_cvt_pk_bf16_f32 v5, v6, v7
	s_waitcnt lgkmcnt(0)
	s_add_u32 s38, s46, 0x110100
	s_addc_u32 s39, s47, 0
	global_store_dwordx4 v189, v[140:143], s[38:39]
	global_store_dwordx4 v190, v[144:147], s[38:39]
	ds_read_b128 v[132:135], v188
	ds_read_b128 v[136:139], v188 offset:1024
	ds_write_b64 v184, v[28:29] offset:2048
	ds_write_b64 v185, v[20:21] offset:2048
	ds_write_b64 v186, v[12:13] offset:2048
	ds_write_b64 v187, v[4:5] offset:2048
	s_waitcnt lgkmcnt(0)
	s_add_u32 s38, s46, 0x880100
	s_addc_u32 s39, s47, 0
	global_store_dwordx4 v189, v[132:135], s[38:39]
	global_store_dwordx4 v190, v[136:139], s[38:39]
	ds_read_b128 v[140:143], v188 offset:2048
	ds_read_b128 v[144:147], v188 offset:3072
	s_waitcnt lgkmcnt(0)
	s_add_u32 s38, s46, 0x990100
	s_addc_u32 s39, s47, 0
	global_store_dwordx4 v189, v[140:143], s[38:39]
	global_store_dwordx4 v190, v[144:147], s[38:39]
	s_branch .LBB0_1095

; DEVI unsigned pk_bf16(float lo, float hi) { unsigned r; asm volatile("v_cvt_pk_bf16_f32 %0, %1, %2" : "=v"(r) : "v"(lo), "v"(hi)); return r; }
; template <class Epi>
; DEVI void gemm_phase(const Params& p, const u16* __restrict__ A, const u16* __restrict__ Bt, const int M, const int N, const int K, const int Msplit, const Epi& epi) {
;     ...
;       if constexpr (Epi::NRM) {
;         nrm = epi.ssq != nullptr && brow < TL;
;         if (nrm) {
;   DEVI void operator()(int row0, int colb, int fr, const f32x4& b0, const f32x4& b1, const f32x4& rv, const bool nrm, const Pre& q) const {
;     ...
;     if (colb < 1280 || colb >= 1920) {
; #pragma unroll
;       for (int n = 0; n < 2; ++n) {
;         const int pc = colb + n * 16 + fr; const int ptc = pc < 1280 ? pc : pc - 640;
;         const f32x4& a = n ? a1 : a0;
;         uint2 o; o.x = pk_bf16(a[0], a[1]); o.y = pk_bf16(a[2], a[3]);
;         *(uint2*)(pt + (size_t)ptc * T + row0) = o;
;       }
.LBB0_1119:
	s_cmpk_lt_u32 s16, 0x80
	s_cbranch_scc0 .Lmy_p4_compiled
	s_cmpk_lt_u32 s40, 0x401
	s_cbranch_scc0 .Lmy_p4_compiled
	s_branch .Lmy_p4_pt
